# v71 + FFN1/SSDIn tile boundary: trailing half's re-offset barrier moved after its tile-header scalar work (overlaps the leading half's header + first read section)
# speedup vs baseline: 1.0102x; 1.0102x over previous
; #define PG8_BAR __builtin_amdgcn_s_barrier()
; template <class Epi, bool ALIGN_EPI = PG8_ALIGN, bool SP2 = PG8_SP2>
; __device__ __forceinline__ void gemm_phase(LAS uchar* lds, const Gemm g, const StaticOrder& S, const Epi& E) {
;     ...
;         const bool has_next = S.next(ui + 1, nxt);
;         const char* nA = has_next ? (const char*)g.A + (size_t)nxt.pm * tstepA : cA; const char* nB = has_next ? (const char*)g.Bt + (size_t)nxt.pn * tstepB : cB;
;         const int tblk = Epi::GROUPS ? 4 : nt;
;     ...
;         if constexpr (ALIGN_EPI) { if (wr == 1) PG8_BAR; }
.LBB0_344:
	s_cmp_lt_u32 s31, 2
	s_cbranch_scc1 .Lxt_skip_344
	s_andn2_b64 vcc, exec, s[8:9]
	s_cbranch_vccnz .Lxt_skip_344
	s_barrier

; __device__ __forceinline__ unsigned pk2(float lo, float hi) { unsigned r; asm("v_cvt_pk_bf16_f32 %0, %1, %2" : "=v"(r) : "v"(lo), "v"(hi)); return r; }
; #define PG8_BAR __builtin_amdgcn_s_barrier()
; template <class Epi, bool ALIGN_EPI = PG8_ALIGN, bool SP2 = PG8_SP2>
; __device__ __forceinline__ void gemm_phase(LAS uchar* lds, const Gemm g, const StaticOrder& S, const Epi& E) {
;     ...
;         if (!has_next) break;
; #pragma unroll
;         for (int a = 0; a < 2; ++a)
; #pragma unroll
;             for (int b = 0; b < 2; ++b)
; #pragma unroll
;                 for (int m = 0; m < 4; ++m)
; #pragma unroll
;                     for (int n = 0; n < 2; ++n) acc[a][b][m][n] = (f32x4){0.f, 0.f, 0.f, 0.f};
;         cur = nxt; cA = nA; cB = nB; ++ui;
;         if constexpr (ALIGN_EPI) { if (wr == 1) PG8_BAR; }
;     __device__ __forceinline__ void operator()(const f32x4 (&acc)[2][2][4][2], const pg8::Unit& u, int wr, int wc, int fr, int fq, int) const {
;         const int row0 = u.pm * 256 + wr * 64 + fr;
;         if (u.pn < 24) {
;             const int col0 = u.pn * 256 + wc * 32 + 8 * fq;
; #pragma unroll
;             for (int ai = 0; ai < 2; ++ai)
; #pragma unroll
;                 for (int m = 0; m < 4; ++m) { bf16_t* rowp = ZX + (size_t)(row0 + ai * 128 + m * 16) * LDZ + col0;
; #pragma unroll
;                     for (int bj = 0; bj < 2; ++bj) { const f32x4 v0 = acc[ai][bj][m][0], v1 = acc[ai][bj][m][1];
;                         u32x4 o; o.x = pk2(v0[0], v0[1]); o.y = pk2(v0[2], v0[3]); o.z = pk2(v1[0], v1[1]); o.w = pk2(v1[2], v1[3]);
;                         *(u32x4*)(rowp + bj * 128) = o; } }
.LBB0_354:
	s_mov_b32 s97, 1
	v_lshl_or_b32 v168, s36, 8, v170
	v_ashrrev_i32_e32 v169, 31, v168
	v_mov_b64_e32 v[166:167], s[90:91]
	v_cvt_pk_bf16_f32 v70, v70, v71
	v_cvt_pk_bf16_f32 v71, v72, v73
	v_cvt_pk_bf16_f32 v72, v66, v67
	v_add_u32_e32 v66, 0x80, v164
	v_mad_i64_i32 v[172:173], s[4:5], v164, s56, v[166:167]
	v_lshlrev_b64 v[168:169], 1, v[168:169]
	v_cvt_pk_bf16_f32 v114, v114, v115
	v_cvt_pk_bf16_f32 v115, v116, v117
	v_cvt_pk_bf16_f32 v116, v106, v107
	v_or_b32_e32 v106, 16, v164
	v_mad_i64_i32 v[66:67], s[4:5], v66, s56, v[166:167]
	v_cvt_pk_bf16_f32 v50, v50, v51
	v_cvt_pk_bf16_f32 v51, v52, v53
	v_cvt_pk_bf16_f32 v52, v42, v43
	v_add_u32_e32 v42, 0x90, v164
	v_lshl_add_u64 v[172:173], v[172:173], 0, v[168:169]
	v_mad_i64_i32 v[106:107], s[4:5], v106, s56, v[166:167]
	v_cvt_pk_bf16_f32 v98, v98, v99
	v_cvt_pk_bf16_f32 v99, v100, v101
	v_cvt_pk_bf16_f32 v100, v90, v91
	v_or_b32_e32 v90, 32, v164
	v_lshl_add_u64 v[66:67], v[66:67], 0, v[168:169]
	v_mad_i64_i32 v[42:43], s[4:5], v42, s56, v[166:167]
	v_cvt_pk_bf16_f32 v34, v34, v35
	v_cvt_pk_bf16_f32 v35, v36, v37
	v_cvt_pk_bf16_f32 v36, v26, v27
	v_add_u32_e32 v26, 0xa0, v164
	v_cvt_pk_bf16_f32 v117, v108, v109
	global_store_dwordx4 v[172:173], v[114:117], off offset:256
	v_mad_i64_i32 v[90:91], s[4:5], v90, s56, v[166:167]
	s_nop 0
	v_lshl_add_u64 v[114:115], v[106:107], 0, v[168:169]
	v_cvt_pk_bf16_f32 v82, v82, v83
	v_cvt_pk_bf16_f32 v83, v84, v85
	v_cvt_pk_bf16_f32 v84, v74, v75
	v_or_b32_e32 v74, 48, v164
	v_cvt_pk_bf16_f32 v53, v44, v45
	global_store_dwordx4 v[66:67], v[50:53], off offset:256
	v_mad_i64_i32 v[26:27], s[4:5], v26, s56, v[166:167]
	s_nop 0
	v_lshl_add_u64 v[50:51], v[42:43], 0, v[168:169]
	v_cvt_pk_bf16_f32 v18, v18, v19
	v_cvt_pk_bf16_f32 v19, v20, v21
	v_cvt_pk_bf16_f32 v20, v10, v11
	v_add_u32_e32 v10, 0xb0, v164
	v_cvt_pk_bf16_f32 v101, v92, v93
	global_store_dwordx4 v[114:115], v[98:101], off offset:256
	v_mad_i64_i32 v[74:75], s[4:5], v74, s56, v[166:167]
	s_nop 0
	v_lshl_add_u64 v[98:99], v[90:91], 0, v[168:169]
	v_cvt_pk_bf16_f32 v37, v28, v29
	global_store_dwordx4 v[50:51], v[34:37], off offset:256
	v_mad_i64_i32 v[10:11], s[4:5], v10, s56, v[166:167]
	s_nop 0
	v_lshl_add_u64 v[34:35], v[26:27], 0, v[168:169]
	v_cvt_pk_bf16_f32 v85, v76, v77
	global_store_dwordx4 v[98:99], v[82:85], off offset:256
	v_cvt_pk_bf16_f32 v21, v12, v13
	global_store_dwordx4 v[34:35], v[18:21], off offset:256
	v_cvt_pk_bf16_f32 v126, v126, v127
	v_cvt_pk_bf16_f32 v127, v128, v129
	v_cvt_pk_bf16_f32 v128, v122, v123
	s_nop 0
	v_lshl_add_u64 v[82:83], v[74:75], 0, v[168:169]
	v_cvt_pk_bf16_f32 v129, v124, v125
	v_lshl_add_u64 v[18:19], v[10:11], 0, v[168:169]
	global_store_dwordx4 v[172:173], v[126:129], off
	v_cvt_pk_bf16_f32 v106, v118, v119
	v_cvt_pk_bf16_f32 v107, v120, v121
	v_cvt_pk_bf16_f32 v108, v110, v111
	v_cvt_pk_bf16_f32 v109, v112, v113
	global_store_dwordx4 v[114:115], v[106:109], off
	v_cvt_pk_bf16_f32 v90, v102, v103
	v_cvt_pk_bf16_f32 v91, v104, v105
	v_cvt_pk_bf16_f32 v92, v94, v95
	v_cvt_pk_bf16_f32 v93, v96, v97
	global_store_dwordx4 v[98:99], v[90:93], off
	v_cvt_pk_bf16_f32 v74, v86, v87
	v_cvt_pk_bf16_f32 v75, v88, v89
	v_cvt_pk_bf16_f32 v76, v78, v79
	v_cvt_pk_bf16_f32 v77, v80, v81
	global_store_dwordx4 v[82:83], v[74:77], off
	v_cvt_pk_bf16_f32 v73, v68, v69
	global_store_dwordx4 v[82:83], v[70:73], off offset:256
	v_cvt_pk_bf16_f32 v62, v62, v63
	v_cvt_pk_bf16_f32 v63, v64, v65
	v_cvt_pk_bf16_f32 v64, v58, v59
	v_cvt_pk_bf16_f32 v65, v60, v61
	global_store_dwordx4 v[66:67], v[62:65], off
	v_cvt_pk_bf16_f32 v42, v54, v55
	v_cvt_pk_bf16_f32 v43, v56, v57
	v_cvt_pk_bf16_f32 v44, v46, v47
	v_cvt_pk_bf16_f32 v45, v48, v49
	global_store_dwordx4 v[50:51], v[42:45], off
	v_cvt_pk_bf16_f32 v26, v38, v39
	v_cvt_pk_bf16_f32 v27, v40, v41
	v_cvt_pk_bf16_f32 v28, v30, v31
	v_cvt_pk_bf16_f32 v29, v32, v33
	global_store_dwordx4 v[34:35], v[26:29], off
	v_cvt_pk_bf16_f32 v10, v22, v23
	v_cvt_pk_bf16_f32 v11, v24, v25
	v_cvt_pk_bf16_f32 v12, v14, v15
	v_cvt_pk_bf16_f32 v13, v16, v17
	global_store_dwordx4 v[18:19], v[10:13], off
	v_cvt_pk_bf16_f32 v6, v6, v7
	v_cvt_pk_bf16_f32 v7, v8, v9
	v_cvt_pk_bf16_f32 v8, v2, v3
	v_cvt_pk_bf16_f32 v9, v4, v5
	global_store_dwordx4 v[18:19], v[6:9], off offset:256
	s_and_b64 vcc, exec, s[0:1]
	s_mov_b64 s[0:1], -1
	s_cbranch_vccnz .LBB0_337
.LBB0_355:
	s_branch .LBB0_336
.LBB0_357:
	s_waitcnt vmcnt(0)
	s_barrier

; #define PG8_BAR __builtin_amdgcn_s_barrier()
; template <class Epi, bool ALIGN_EPI = PG8_ALIGN, bool SP2 = PG8_SP2>
; __device__ __forceinline__ void gemm_phase(LAS uchar* lds, const Gemm g, const StaticOrder& S, const Epi& E) {
;     ...
;         const bool has_next = S.next(ui + 1, nxt);
;         const char* nA = has_next ? (const char*)g.A + (size_t)nxt.pm * tstepA : cA; const char* nB = has_next ? (const char*)g.Bt + (size_t)nxt.pn * tstepB : cB;
;         const int tblk = Epi::GROUPS ? 4 : nt;
;     ...
;         if constexpr (ALIGN_EPI) { if (wr == 1) PG8_BAR; }
.LBB0_1049:
	s_cmp_lt_u32 s29, 2
	s_cbranch_scc1 .Lxt_skip_1049
	s_andn2_b64 vcc, exec, s[6:7]
	s_cbranch_vccnz .Lxt_skip_1049
	s_barrier

; __device__ __forceinline__ u32x4 pack8(const float (&o)[8]) { u32x4 r; r.x = pk2(o[0], o[1]); r.y = pk2(o[2], o[3]); r.z = pk2(o[4], o[5]); r.w = pk2(o[6], o[7]); return r; }
; __device__ __forceinline__ float silu_f(float v) { return v * __builtin_amdgcn_rcpf(1.f + __expf(-v)); }
;     __device__ __forceinline__ void operator()(const f32x4 (&acc)[2][2][4][2], const pg8::Unit& u, int wr, int wc, int fr, int fq, int) const {
;         const int row0 = u.pm * 256 + wr * 64 + fr, col0 = u.pn * 128 + wc * 32 + 8 * fq;
; #pragma unroll
;         for (int ai = 0; ai < 2; ++ai)
; #pragma unroll
;             for (int m = 0; m < 4; ++m) { bf16_t* rowp = O + (size_t)(row0 + ai * 128 + m * 16) * DFF + col0;
;                 float r[8];
; #pragma unroll
;                 for (int n = 0; n < 2; ++n)
; #pragma unroll
;                     for (int i = 0; i < 4; ++i) { const float gt = acc[ai][0][m][n][i], up = acc[ai][1][m][n][i]; r[n * 4 + i] = silu_f(gt) * up; }
;                 *(u32x4*)rowp = pack8(r); }
.LBB0_1053:
	v_lshl_or_b32 v166, s35, 7, v162
	v_lshl_add_u32 v164, s34, 8, v1
	v_mov_b32_e32 v252, 0xbfb8aa3b
	v_mov_b32_e32 v253, 0xbfb8aa3b
	v_ashrrev_i32_e32 v167, 31, v166
	v_mov_b64_e32 v[160:161], s[90:91]
	v_mov_b32_e32 v250, 1.0
	v_mov_b32_e32 v251, 1.0
	v_lshlrev_b64 v[166:167], 1, v[166:167]
	s_and_b64 vcc, exec, s[4:5]
	v_lshl_add_u64 v[160:161], v[160:161], 0, v[166:167]
	v_mad_i64_i32 v[200:201], s[12:13], v164, s80, v[160:161]
	v_pk_mul_f32 v[122:123], v[126:127], v[122:123]
	v_pk_mul_f32 v[124:125], v[128:129], v[124:125]
	v_pk_mul_f32 v[114:115], v[118:119], v[114:115]
	v_pk_mul_f32 v[116:117], v[120:121], v[116:117]
	v_pk_mul_f32 v[126:127], v[126:127], v[252:253]
	v_pk_mul_f32 v[128:129], v[128:129], v[252:253]
	v_pk_mul_f32 v[118:119], v[118:119], v[252:253]
	v_pk_mul_f32 v[120:121], v[120:121], v[252:253]
	v_exp_f32_e32 v126, v126
	v_exp_f32_e32 v127, v127
	v_exp_f32_e32 v128, v128
	v_exp_f32_e32 v129, v129
	v_exp_f32_e32 v118, v118
	v_exp_f32_e32 v119, v119
	v_exp_f32_e32 v120, v120
	v_exp_f32_e32 v121, v121
	v_pk_add_f32 v[126:127], v[126:127], v[250:251]
	v_pk_add_f32 v[128:129], v[128:129], v[250:251]
	v_pk_add_f32 v[118:119], v[118:119], v[250:251]
	v_pk_add_f32 v[120:121], v[120:121], v[250:251]
	v_rcp_f32_e32 v126, v126
	v_rcp_f32_e32 v127, v127
	v_rcp_f32_e32 v128, v128
	v_rcp_f32_e32 v129, v129
	v_rcp_f32_e32 v118, v118
	v_rcp_f32_e32 v119, v119
	v_rcp_f32_e32 v120, v120
	v_rcp_f32_e32 v121, v121
	v_pk_mul_f32 v[122:123], v[122:123], v[126:127]
	v_pk_mul_f32 v[124:125], v[124:125], v[128:129]
	v_pk_mul_f32 v[114:115], v[114:115], v[118:119]
	v_pk_mul_f32 v[116:117], v[116:117], v[120:121]
	v_cvt_pk_bf16_f32 v230, v122, v123
	v_cvt_pk_bf16_f32 v231, v124, v125
	v_cvt_pk_bf16_f32 v232, v114, v115
	v_cvt_pk_bf16_f32 v233, v116, v117
	global_store_dwordx4 v[200:201], v[230:233], off
	v_add_u32_e32 v221, 16, v164
	v_mad_i64_i32 v[202:203], s[12:13], v221, s80, v[160:161]
	v_pk_mul_f32 v[106:107], v[110:111], v[106:107]
	v_pk_mul_f32 v[108:109], v[112:113], v[108:109]
	v_pk_mul_f32 v[98:99], v[102:103], v[98:99]
	v_pk_mul_f32 v[100:101], v[104:105], v[100:101]
	v_pk_mul_f32 v[110:111], v[110:111], v[252:253]
	v_pk_mul_f32 v[112:113], v[112:113], v[252:253]
	v_pk_mul_f32 v[102:103], v[102:103], v[252:253]
	v_pk_mul_f32 v[104:105], v[104:105], v[252:253]
	v_exp_f32_e32 v110, v110
	v_exp_f32_e32 v111, v111
	v_exp_f32_e32 v112, v112
	v_exp_f32_e32 v113, v113
	v_exp_f32_e32 v102, v102
	v_exp_f32_e32 v103, v103
	v_exp_f32_e32 v104, v104
	v_exp_f32_e32 v105, v105
	v_pk_add_f32 v[110:111], v[110:111], v[250:251]
	v_pk_add_f32 v[112:113], v[112:113], v[250:251]
	v_pk_add_f32 v[102:103], v[102:103], v[250:251]
	v_pk_add_f32 v[104:105], v[104:105], v[250:251]
	v_rcp_f32_e32 v110, v110
	v_rcp_f32_e32 v111, v111
	v_rcp_f32_e32 v112, v112
	v_rcp_f32_e32 v113, v113
	v_rcp_f32_e32 v102, v102
	v_rcp_f32_e32 v103, v103
	v_rcp_f32_e32 v104, v104
	v_rcp_f32_e32 v105, v105
	v_pk_mul_f32 v[106:107], v[106:107], v[110:111]
	v_pk_mul_f32 v[108:109], v[108:109], v[112:113]
	v_pk_mul_f32 v[98:99], v[98:99], v[102:103]
	v_pk_mul_f32 v[100:101], v[100:101], v[104:105]
	v_cvt_pk_bf16_f32 v234, v106, v107
	v_cvt_pk_bf16_f32 v235, v108, v109
	v_cvt_pk_bf16_f32 v236, v98, v99
	v_cvt_pk_bf16_f32 v237, v100, v101
	global_store_dwordx4 v[202:203], v[234:237], off
	v_add_u32_e32 v222, 32, v164
	v_mad_i64_i32 v[204:205], s[12:13], v222, s80, v[160:161]
	v_pk_mul_f32 v[90:91], v[94:95], v[90:91]
	v_pk_mul_f32 v[92:93], v[96:97], v[92:93]
	v_pk_mul_f32 v[82:83], v[86:87], v[82:83]
	v_pk_mul_f32 v[84:85], v[88:89], v[84:85]
	v_pk_mul_f32 v[94:95], v[94:95], v[252:253]
	v_pk_mul_f32 v[96:97], v[96:97], v[252:253]
	v_pk_mul_f32 v[86:87], v[86:87], v[252:253]
	v_pk_mul_f32 v[88:89], v[88:89], v[252:253]
	v_exp_f32_e32 v94, v94
	v_exp_f32_e32 v95, v95
	v_exp_f32_e32 v96, v96
	v_exp_f32_e32 v97, v97
	v_exp_f32_e32 v86, v86
	v_exp_f32_e32 v87, v87
	v_exp_f32_e32 v88, v88
	v_exp_f32_e32 v89, v89
	v_pk_add_f32 v[94:95], v[94:95], v[250:251]
	v_pk_add_f32 v[96:97], v[96:97], v[250:251]
	v_pk_add_f32 v[86:87], v[86:87], v[250:251]
	v_pk_add_f32 v[88:89], v[88:89], v[250:251]
	v_rcp_f32_e32 v94, v94
	v_rcp_f32_e32 v95, v95
	v_rcp_f32_e32 v96, v96
	v_rcp_f32_e32 v97, v97
	v_rcp_f32_e32 v86, v86
	v_rcp_f32_e32 v87, v87
	v_rcp_f32_e32 v88, v88
	v_rcp_f32_e32 v89, v89
	v_pk_mul_f32 v[90:91], v[90:91], v[94:95]
	v_pk_mul_f32 v[92:93], v[92:93], v[96:97]
	v_pk_mul_f32 v[82:83], v[82:83], v[86:87]
	v_pk_mul_f32 v[84:85], v[84:85], v[88:89]
	v_cvt_pk_bf16_f32 v238, v90, v91
	v_cvt_pk_bf16_f32 v239, v92, v93
	v_cvt_pk_bf16_f32 v240, v82, v83
	v_cvt_pk_bf16_f32 v241, v84, v85
	global_store_dwordx4 v[204:205], v[238:241], off
	v_add_u32_e32 v223, 48, v164
	v_mad_i64_i32 v[206:207], s[12:13], v223, s80, v[160:161]
	v_pk_mul_f32 v[74:75], v[78:79], v[74:75]
	v_pk_mul_f32 v[76:77], v[80:81], v[76:77]
	v_pk_mul_f32 v[66:67], v[70:71], v[66:67]
	v_pk_mul_f32 v[68:69], v[72:73], v[68:69]
	v_pk_mul_f32 v[78:79], v[78:79], v[252:253]
	v_pk_mul_f32 v[80:81], v[80:81], v[252:253]
	v_pk_mul_f32 v[70:71], v[70:71], v[252:253]
	v_pk_mul_f32 v[72:73], v[72:73], v[252:253]
	v_exp_f32_e32 v78, v78
	v_exp_f32_e32 v79, v79
	v_exp_f32_e32 v80, v80
	v_exp_f32_e32 v81, v81
	v_exp_f32_e32 v70, v70
	v_exp_f32_e32 v71, v71
	v_exp_f32_e32 v72, v72
	v_exp_f32_e32 v73, v73
	v_pk_add_f32 v[78:79], v[78:79], v[250:251]
	v_pk_add_f32 v[80:81], v[80:81], v[250:251]
	v_pk_add_f32 v[70:71], v[70:71], v[250:251]
	v_pk_add_f32 v[72:73], v[72:73], v[250:251]
	v_rcp_f32_e32 v78, v78
	v_rcp_f32_e32 v79, v79
	v_rcp_f32_e32 v80, v80
	v_rcp_f32_e32 v81, v81
	v_rcp_f32_e32 v70, v70
	v_rcp_f32_e32 v71, v71
; __device__ __forceinline__ u32x4 pack8(const float (&o)[8]) { u32x4 r; r.x = pk2(o[0], o[1]); r.y = pk2(o[2], o[3]); r.z = pk2(o[4], o[5]); r.w = pk2(o[6], o[7]); return r; }
; __device__ __forceinline__ float silu_f(float v) { return v * __builtin_amdgcn_rcpf(1.f + __expf(-v)); }
; #define PG8_BAR __builtin_amdgcn_s_barrier()
; template <class Epi, bool ALIGN_EPI = PG8_ALIGN, bool SP2 = PG8_SP2>
; __device__ __forceinline__ void gemm_phase(LAS uchar* lds, const Gemm g, const StaticOrder& S, const Epi& E) {
;     ...
;         cur = nxt; cA = nA; cB = nB; ++ui;
;         if constexpr (ALIGN_EPI) { if (wr == 1) PG8_BAR; }
;     __device__ __forceinline__ void operator()(const f32x4 (&acc)[2][2][4][2], const pg8::Unit& u, int wr, int wc, int fr, int fq, int) const {
;         const int row0 = u.pm * 256 + wr * 64 + fr, col0 = u.pn * 128 + wc * 32 + 8 * fq;
; #pragma unroll
;         for (int ai = 0; ai < 2; ++ai)
; #pragma unroll
;             for (int m = 0; m < 4; ++m) { bf16_t* rowp = O + (size_t)(row0 + ai * 128 + m * 16) * DFF + col0;
;                 float r[8];
; #pragma unroll
;                 for (int n = 0; n < 2; ++n)
; #pragma unroll
;                     for (int i = 0; i < 4; ++i) { const float gt = acc[ai][0][m][n][i], up = acc[ai][1][m][n][i]; r[n * 4 + i] = silu_f(gt) * up; }
;                 *(u32x4*)rowp = pack8(r); }
	v_rcp_f32_e32 v72, v72
	v_rcp_f32_e32 v73, v73
	v_pk_mul_f32 v[74:75], v[74:75], v[78:79]
	v_pk_mul_f32 v[76:77], v[76:77], v[80:81]
	v_pk_mul_f32 v[66:67], v[66:67], v[70:71]
	v_pk_mul_f32 v[68:69], v[68:69], v[72:73]
	v_cvt_pk_bf16_f32 v242, v74, v75
	v_cvt_pk_bf16_f32 v243, v76, v77
	v_cvt_pk_bf16_f32 v244, v66, v67
	v_cvt_pk_bf16_f32 v245, v68, v69
	global_store_dwordx4 v[206:207], v[242:245], off
	v_add_u32_e32 v224, 128, v164
	v_mad_i64_i32 v[208:209], s[12:13], v224, s80, v[160:161]
	v_pk_mul_f32 v[58:59], v[62:63], v[58:59]
	v_pk_mul_f32 v[60:61], v[64:65], v[60:61]
	v_pk_mul_f32 v[50:51], v[54:55], v[50:51]
	v_pk_mul_f32 v[52:53], v[56:57], v[52:53]
	v_pk_mul_f32 v[62:63], v[62:63], v[252:253]
	v_pk_mul_f32 v[64:65], v[64:65], v[252:253]
	v_pk_mul_f32 v[54:55], v[54:55], v[252:253]
	v_pk_mul_f32 v[56:57], v[56:57], v[252:253]
	v_exp_f32_e32 v62, v62
	v_exp_f32_e32 v63, v63
	v_exp_f32_e32 v64, v64
	v_exp_f32_e32 v65, v65
	v_exp_f32_e32 v54, v54
	v_exp_f32_e32 v55, v55
	v_exp_f32_e32 v56, v56
	v_exp_f32_e32 v57, v57
	v_pk_add_f32 v[62:63], v[62:63], v[250:251]
	v_pk_add_f32 v[64:65], v[64:65], v[250:251]
	v_pk_add_f32 v[54:55], v[54:55], v[250:251]
	v_pk_add_f32 v[56:57], v[56:57], v[250:251]
	v_rcp_f32_e32 v62, v62
	v_rcp_f32_e32 v63, v63
	v_rcp_f32_e32 v64, v64
	v_rcp_f32_e32 v65, v65
	v_rcp_f32_e32 v54, v54
	v_rcp_f32_e32 v55, v55
	v_rcp_f32_e32 v56, v56
	v_rcp_f32_e32 v57, v57
	v_pk_mul_f32 v[58:59], v[58:59], v[62:63]
	v_pk_mul_f32 v[60:61], v[60:61], v[64:65]
	v_pk_mul_f32 v[50:51], v[50:51], v[54:55]
	v_pk_mul_f32 v[52:53], v[52:53], v[56:57]
	v_cvt_pk_bf16_f32 v230, v58, v59
	v_cvt_pk_bf16_f32 v231, v60, v61
	v_cvt_pk_bf16_f32 v232, v50, v51
	v_cvt_pk_bf16_f32 v233, v52, v53
	global_store_dwordx4 v[208:209], v[230:233], off
	v_add_u32_e32 v225, 144, v164
	v_mad_i64_i32 v[210:211], s[12:13], v225, s80, v[160:161]
	v_pk_mul_f32 v[42:43], v[46:47], v[42:43]
	v_pk_mul_f32 v[44:45], v[48:49], v[44:45]
	v_pk_mul_f32 v[34:35], v[38:39], v[34:35]
	v_pk_mul_f32 v[36:37], v[40:41], v[36:37]
	v_pk_mul_f32 v[46:47], v[46:47], v[252:253]
	v_pk_mul_f32 v[48:49], v[48:49], v[252:253]
	v_pk_mul_f32 v[38:39], v[38:39], v[252:253]
	v_pk_mul_f32 v[40:41], v[40:41], v[252:253]
	v_exp_f32_e32 v46, v46
	v_exp_f32_e32 v47, v47
	v_exp_f32_e32 v48, v48
	v_exp_f32_e32 v49, v49
	v_exp_f32_e32 v38, v38
	v_exp_f32_e32 v39, v39
	v_exp_f32_e32 v40, v40
	v_exp_f32_e32 v41, v41
	v_pk_add_f32 v[46:47], v[46:47], v[250:251]
	v_pk_add_f32 v[48:49], v[48:49], v[250:251]
	v_pk_add_f32 v[38:39], v[38:39], v[250:251]
	v_pk_add_f32 v[40:41], v[40:41], v[250:251]
	v_rcp_f32_e32 v46, v46
	v_rcp_f32_e32 v47, v47
	v_rcp_f32_e32 v48, v48
	v_rcp_f32_e32 v49, v49
	v_rcp_f32_e32 v38, v38
	v_rcp_f32_e32 v39, v39
	v_rcp_f32_e32 v40, v40
	v_rcp_f32_e32 v41, v41
	v_pk_mul_f32 v[42:43], v[42:43], v[46:47]
	v_pk_mul_f32 v[44:45], v[44:45], v[48:49]
	v_pk_mul_f32 v[34:35], v[34:35], v[38:39]
	v_pk_mul_f32 v[36:37], v[36:37], v[40:41]
	v_cvt_pk_bf16_f32 v234, v42, v43
	v_cvt_pk_bf16_f32 v235, v44, v45
	v_cvt_pk_bf16_f32 v236, v34, v35
	v_cvt_pk_bf16_f32 v237, v36, v37
	global_store_dwordx4 v[210:211], v[234:237], off
	v_add_u32_e32 v226, 160, v164
	v_mad_i64_i32 v[212:213], s[12:13], v226, s80, v[160:161]
	v_pk_mul_f32 v[26:27], v[30:31], v[26:27]
	v_pk_mul_f32 v[28:29], v[32:33], v[28:29]
	v_pk_mul_f32 v[18:19], v[22:23], v[18:19]
	v_pk_mul_f32 v[20:21], v[24:25], v[20:21]
	v_pk_mul_f32 v[30:31], v[30:31], v[252:253]
	v_pk_mul_f32 v[32:33], v[32:33], v[252:253]
	v_pk_mul_f32 v[22:23], v[22:23], v[252:253]
	v_pk_mul_f32 v[24:25], v[24:25], v[252:253]
	v_exp_f32_e32 v30, v30
	v_exp_f32_e32 v31, v31
	v_exp_f32_e32 v32, v32
	v_exp_f32_e32 v33, v33
	v_exp_f32_e32 v22, v22
	v_exp_f32_e32 v23, v23
	v_exp_f32_e32 v24, v24
	v_exp_f32_e32 v25, v25
	v_pk_add_f32 v[30:31], v[30:31], v[250:251]
	v_pk_add_f32 v[32:33], v[32:33], v[250:251]
	v_pk_add_f32 v[22:23], v[22:23], v[250:251]
	v_pk_add_f32 v[24:25], v[24:25], v[250:251]
	v_rcp_f32_e32 v30, v30
	v_rcp_f32_e32 v31, v31
	v_rcp_f32_e32 v32, v32
	v_rcp_f32_e32 v33, v33
	v_rcp_f32_e32 v22, v22
	v_rcp_f32_e32 v23, v23
	v_rcp_f32_e32 v24, v24
	v_rcp_f32_e32 v25, v25
	v_pk_mul_f32 v[26:27], v[26:27], v[30:31]
	v_pk_mul_f32 v[28:29], v[28:29], v[32:33]
	v_pk_mul_f32 v[18:19], v[18:19], v[22:23]
	v_pk_mul_f32 v[20:21], v[20:21], v[24:25]
	v_cvt_pk_bf16_f32 v238, v26, v27
	v_cvt_pk_bf16_f32 v239, v28, v29
	v_cvt_pk_bf16_f32 v240, v18, v19
	v_cvt_pk_bf16_f32 v241, v20, v21
	global_store_dwordx4 v[212:213], v[238:241], off
	v_add_u32_e32 v227, 176, v164
	v_mad_i64_i32 v[214:215], s[12:13], v227, s80, v[160:161]
	v_pk_mul_f32 v[10:11], v[14:15], v[10:11]
	v_pk_mul_f32 v[12:13], v[16:17], v[12:13]
	v_pk_mul_f32 v[2:3], v[6:7], v[2:3]
	v_pk_mul_f32 v[4:5], v[8:9], v[4:5]
	v_pk_mul_f32 v[14:15], v[14:15], v[252:253]
	v_pk_mul_f32 v[16:17], v[16:17], v[252:253]
	v_pk_mul_f32 v[6:7], v[6:7], v[252:253]
	v_pk_mul_f32 v[8:9], v[8:9], v[252:253]
	v_exp_f32_e32 v14, v14
	v_exp_f32_e32 v15, v15
	v_exp_f32_e32 v16, v16
	v_exp_f32_e32 v17, v17
	v_exp_f32_e32 v6, v6
	v_exp_f32_e32 v7, v7
	v_exp_f32_e32 v8, v8
	v_exp_f32_e32 v9, v9
	v_pk_add_f32 v[14:15], v[14:15], v[250:251]
	v_pk_add_f32 v[16:17], v[16:17], v[250:251]
	v_pk_add_f32 v[6:7], v[6:7], v[250:251]
	v_pk_add_f32 v[8:9], v[8:9], v[250:251]
	v_rcp_f32_e32 v14, v14
	v_rcp_f32_e32 v15, v15
	v_rcp_f32_e32 v16, v16
	v_rcp_f32_e32 v17, v17
	v_rcp_f32_e32 v6, v6
	v_rcp_f32_e32 v7, v7
	v_rcp_f32_e32 v8, v8
	v_rcp_f32_e32 v9, v9
	v_pk_mul_f32 v[10:11], v[10:11], v[14:15]
	v_pk_mul_f32 v[12:13], v[12:13], v[16:17]
	v_pk_mul_f32 v[2:3], v[2:3], v[6:7]
	v_pk_mul_f32 v[4:5], v[4:5], v[8:9]
	v_cvt_pk_bf16_f32 v242, v10, v11
	v_cvt_pk_bf16_f32 v243, v12, v13
	v_cvt_pk_bf16_f32 v244, v2, v3
	v_cvt_pk_bf16_f32 v245, v4, v5
	global_store_dwordx4 v[214:215], v[242:245], off
	s_mov_b64 s[12:13], -1
	s_cbranch_vccnz .LBB0_1042
	s_branch .LBB0_1041
